# v112 + one static priority raise for the younger co-resident block (bid>=256) after each SwiGLU tile, reset in phase-18 idle path
# baseline (speedup 1.0000x reference)
; __device__ __forceinline__ void prep_weights(const Params& p, int layer, int which, float* tile, int bid, int nb) {
;   bf16_t* wb = (bf16_t*)(p.ws + OFF_WB);
;   for (int s = 0; s < 2; s++) {
;     if (!((which >> s) & 1)) continue;
;     const float* win = p.ffn_w_in + (size_t)(layer * 2 + s) * 1024 * 5632;
;     const float* wout = p.ffn_w_out + (size_t)(layer * 2 + s) * 2816 * 1024;
;     bf16_t* din = wb + (s ? W0_FIN_B : W0_FIN_A);
;     bf16_t* dout = wb + (s ? W0_FOUT_B : W0_FOUT_A);
;     wjob_run(win, din, 5632, 0, 5632, 5632, 0, 1024, 0, 1024, 1024, 1, 0, nullptr, tile, bid, nb);
;     wjob_run(wout, dout, 1024, 0, 1024, 1024, 0, 2816, 0, 2816, 2816, 0, 0, nullptr, tile, bid, nb);
; __device__ __forceinline__ void run_phase(const Params& p, int ph, char* smraw, int bid, int nb) {
;     ...
;     case 10:
;       if (nb == 512 && bid >= 256) prep_weights(p, 1, 2, smf, bid - 256, 256);
;       else { if (nb != 512) prep_weights(p, 1, 2, smf, bid, nb); rwkv_phase(p, smf, bid, nb); }
.LBB0_534:
	s_and_b64 vcc, exec, s[4:5]
	s_cbranch_vccz .LBB0_579
	s_setprio 0
	v_readlane_b32 s2, v244, 27
	v_lshrrev_b32_e32 v32, 6, v2
	v_and_b32_e32 v33, 63, v2
	v_readlane_b32 s6, v247, 3
	v_readlane_b32 s7, v247, 4
	v_readfirstlane_b32 s4, v32
	s_addk_i32 s2, 0xff00
	s_lshl_b32 s2, s2, 2
	s_add_i32 s2, s2, s4
	s_movk_i32 s5, 0x400
	s_add_u32 s6, s6, 0x8200000
	s_addc_u32 s7, s7, 0

; __device__ __forceinline__ float siluf_(float x) { return x * __builtin_amdgcn_rcpf(1.f + __expf(-x)); }
;     ...
;           for (int mi = 0; mi < MI; mi++)
; #pragma unroll
;             for (int ni = 0; ni < 4; ni++)
;               acc[mi][ni] = __builtin_amdgcn_mfma_f32_16x16x32_bf16(bfr[ni], af[mi], acc[mi][ni], 0, 0, 0);
;     ...
;         } else if constexpr (EPI == EPI_SWIGLU) {
; #pragma unroll
;           for (int np = 0; np < 2; np++) {
;             const unsigned hc = ((unsigned)(n0 + wn * 64) >> 1) + np * 16 + fq * 4;
;             const f32x4 g = acc[mi][2 * np], u = acc[mi][2 * np + 1];
;             uint2 o;
;             o.x = pack2(siluf_(g[0]) * u[0], siluf_(g[1]) * u[1]);
;             o.y = pack2(siluf_(g[2]) * u[2], siluf_(g[3]) * u[3]);
;             *(uint2*)(e.b0 + (row * (unsigned)DFF + hc)) = o;
;           }
.Lsw_last:
	v_mfma_f32_16x16x32_bf16 v[134:137], v[194:197], v[156:159], v[134:137]
	v_mfma_f32_16x16x32_bf16 v[130:133], v[198:201], v[156:159], v[130:133]
	v_mfma_f32_16x16x32_bf16 v[126:129], v[202:205], v[156:159], v[126:129]
	v_mfma_f32_16x16x32_bf16 v[122:125], v[226:229], v[156:159], v[122:125]
	v_mfma_f32_16x16x32_bf16 v[118:121], v[194:197], v[166:169], v[118:121]
	v_mfma_f32_16x16x32_bf16 v[114:117], v[198:201], v[166:169], v[114:117]
	v_mfma_f32_16x16x32_bf16 v[110:113], v[202:205], v[166:169], v[110:113]
	v_mfma_f32_16x16x32_bf16 v[106:109], v[226:229], v[166:169], v[106:109]
	v_mfma_f32_16x16x32_bf16 v[102:105], v[194:197], v[170:173], v[102:105]
	v_mfma_f32_16x16x32_bf16 v[98:101], v[198:201], v[170:173], v[98:101]
	v_mfma_f32_16x16x32_bf16 v[94:97], v[202:205], v[170:173], v[94:97]
	v_mfma_f32_16x16x32_bf16 v[90:93], v[226:229], v[170:173], v[90:93]
	v_mfma_f32_16x16x32_bf16 v[86:89], v[194:197], v[174:177], v[86:89]
	v_mfma_f32_16x16x32_bf16 v[82:85], v[198:201], v[174:177], v[82:85]
	v_mfma_f32_16x16x32_bf16 v[78:81], v[202:205], v[174:177], v[78:81]
	v_mfma_f32_16x16x32_bf16 v[74:77], v[226:229], v[174:177], v[74:77]
	v_mfma_f32_16x16x32_bf16 v[70:73], v[194:197], v[178:181], v[70:73]
	v_mfma_f32_16x16x32_bf16 v[66:69], v[198:201], v[178:181], v[66:69]
	v_mfma_f32_16x16x32_bf16 v[62:65], v[202:205], v[178:181], v[62:65]
	v_mfma_f32_16x16x32_bf16 v[58:61], v[226:229], v[178:181], v[58:61]
	v_mfma_f32_16x16x32_bf16 v[54:57], v[194:197], v[182:185], v[54:57]
	v_mfma_f32_16x16x32_bf16 v[50:53], v[198:201], v[182:185], v[50:53]
	v_mfma_f32_16x16x32_bf16 v[46:49], v[202:205], v[182:185], v[46:49]
	v_mfma_f32_16x16x32_bf16 v[42:45], v[226:229], v[182:185], v[42:45]
	v_mfma_f32_16x16x32_bf16 v[38:41], v[194:197], v[186:189], v[38:41]
	v_mfma_f32_16x16x32_bf16 v[34:37], v[198:201], v[186:189], v[34:37]
	v_mfma_f32_16x16x32_bf16 v[30:33], v[202:205], v[186:189], v[30:33]
	v_mfma_f32_16x16x32_bf16 v[26:29], v[226:229], v[186:189], v[26:29]
	v_mfma_f32_16x16x32_bf16 v[22:25], v[194:197], v[190:193], v[22:25]
	v_mfma_f32_16x16x32_bf16 v[18:21], v[198:201], v[190:193], v[18:21]
	v_mfma_f32_16x16x32_bf16 v[14:17], v[202:205], v[190:193], v[14:17]
	v_mfma_f32_16x16x32_bf16 v[10:13], v[226:229], v[190:193], v[10:13]
	s_setprio 2
	v_or_b32_e32 v8, s8, v148
	v_lshrrev_b32_e32 v8, 1, v8
	v_add_u32_e32 v142, s7, v150
	v_or_b32_e32 v8, v8, v149
	s_movk_i32 s4, 0xb00
	v_mad_u64_u32 v[142:143], s[4:5], v142, s4, v[8:9]
	v_bfe_u32 v144, v2, 4, 1
	v_mul_u32_u24_e32 v144, 12, v144
	s_nop 0
	v_add_u32_e32 v142, v142, v144
	v_mul_f32_e32 v174, 0xbfb8aa3b, v134
	v_mul_f32_e32 v175, 0xbfb8aa3b, v135
	v_mul_f32_e32 v176, 0xbfb8aa3b, v136
	v_mul_f32_e32 v177, 0xbfb8aa3b, v137
	v_mul_f32_e32 v178, 0xbfb8aa3b, v126
	v_mul_f32_e32 v179, 0xbfb8aa3b, v127
	v_mul_f32_e32 v180, 0xbfb8aa3b, v128
	v_mul_f32_e32 v181, 0xbfb8aa3b, v129
	v_exp_f32_e32 v174, v174
	v_exp_f32_e32 v175, v175
	v_exp_f32_e32 v176, v176
	v_exp_f32_e32 v177, v177
	v_exp_f32_e32 v178, v178
	v_exp_f32_e32 v179, v179
	v_exp_f32_e32 v180, v180
	v_exp_f32_e32 v181, v181
	v_add_f32_e32 v174, 1.0, v174
	v_add_f32_e32 v175, 1.0, v175
	v_add_f32_e32 v176, 1.0, v176
	v_add_f32_e32 v177, 1.0, v177
	v_add_f32_e32 v178, 1.0, v178
	v_add_f32_e32 v179, 1.0, v179
	v_add_f32_e32 v180, 1.0, v180
	v_add_f32_e32 v181, 1.0, v181
	v_rcp_f32_e32 v174, v174
	v_rcp_f32_e32 v175, v175
	v_rcp_f32_e32 v176, v176
	v_rcp_f32_e32 v177, v177
	v_rcp_f32_e32 v178, v178
	v_rcp_f32_e32 v179, v179
	v_rcp_f32_e32 v180, v180
	v_rcp_f32_e32 v181, v181
	v_mov_b32_e32 v8, v142
	v_pk_mul_f32 v[134:135], v[134:135], v[174:175]
	v_pk_mul_f32 v[136:137], v[136:137], v[176:177]
	v_pk_mul_f32 v[126:127], v[126:127], v[178:179]
	v_pk_mul_f32 v[128:129], v[128:129], v[180:181]
	v_lshl_add_u64 v[182:183], v[8:9], 1, s[52:53]
	v_pk_mul_f32 v[130:131], v[130:131], v[134:135]
	v_pk_mul_f32 v[132:133], v[132:133], v[136:137]
	v_pk_mul_f32 v[122:123], v[122:123], v[126:127]
	v_pk_mul_f32 v[124:125], v[124:125], v[128:129]
	v_cvt_pk_bf16_f32 v166, v130, v131
	v_cvt_pk_bf16_f32 v167, v132, v133
	v_cvt_pk_bf16_f32 v168, v122, v123
	v_cvt_pk_bf16_f32 v169, v124, v125
	s_nop 1
	v_permlane16_swap_b32 v166, v168
	v_permlane16_swap_b32 v167, v169
	s_nop 1
	global_store_dwordx4 v[182:183], v[166:169], off
	v_mul_f32_e32 v174, 0xbfb8aa3b, v118
	v_mul_f32_e32 v175, 0xbfb8aa3b, v119
	v_mul_f32_e32 v176, 0xbfb8aa3b, v120
	v_mul_f32_e32 v177, 0xbfb8aa3b, v121
	v_mul_f32_e32 v178, 0xbfb8aa3b, v110
	v_mul_f32_e32 v179, 0xbfb8aa3b, v111
	v_mul_f32_e32 v180, 0xbfb8aa3b, v112
	v_mul_f32_e32 v181, 0xbfb8aa3b, v113
	v_exp_f32_e32 v174, v174
	v_exp_f32_e32 v175, v175
	v_exp_f32_e32 v176, v176
	v_exp_f32_e32 v177, v177
	v_exp_f32_e32 v178, v178
	v_exp_f32_e32 v179, v179
	v_exp_f32_e32 v180, v180
	v_exp_f32_e32 v181, v181
	v_add_f32_e32 v174, 1.0, v174
	v_add_f32_e32 v175, 1.0, v175
	v_add_f32_e32 v176, 1.0, v176
	v_add_f32_e32 v177, 1.0, v177
	v_add_f32_e32 v178, 1.0, v178
	v_add_f32_e32 v179, 1.0, v179
	v_add_f32_e32 v180, 1.0, v180
	v_add_f32_e32 v181, 1.0, v181
	v_rcp_f32_e32 v174, v174
	v_rcp_f32_e32 v175, v175
	v_rcp_f32_e32 v176, v176
	v_rcp_f32_e32 v177, v177
	v_rcp_f32_e32 v178, v178
	v_rcp_f32_e32 v179, v179
	v_rcp_f32_e32 v180, v180
	v_rcp_f32_e32 v181, v181
	v_add_u32_e32 v8, 0xb000, v142
	v_pk_mul_f32 v[118:119], v[118:119], v[174:175]
	v_pk_mul_f32 v[120:121], v[120:121], v[176:177]
	v_pk_mul_f32 v[110:111], v[110:111], v[178:179]
	v_pk_mul_f32 v[112:113], v[112:113], v[180:181]
	v_lshl_add_u64 v[184:185], v[8:9], 1, s[52:53]
	v_pk_mul_f32 v[114:115], v[114:115], v[118:119]
	v_pk_mul_f32 v[116:117], v[116:117], v[120:121]
	v_pk_mul_f32 v[106:107], v[106:107], v[110:111]
; __device__ __forceinline__ float siluf_(float x) { return x * __builtin_amdgcn_rcpf(1.f + __expf(-x)); }
;     ...
;         } else if constexpr (EPI == EPI_SWIGLU) {
; #pragma unroll
;           for (int np = 0; np < 2; np++) {
;             const unsigned hc = ((unsigned)(n0 + wn * 64) >> 1) + np * 16 + fq * 4;
;             const f32x4 g = acc[mi][2 * np], u = acc[mi][2 * np + 1];
;             uint2 o;
;             o.x = pack2(siluf_(g[0]) * u[0], siluf_(g[1]) * u[1]);
;             o.y = pack2(siluf_(g[2]) * u[2], siluf_(g[3]) * u[3]);
;             *(uint2*)(e.b0 + (row * (unsigned)DFF + hc)) = o;
;           }
	v_pk_mul_f32 v[108:109], v[108:109], v[112:113]
	v_cvt_pk_bf16_f32 v170, v114, v115
	v_cvt_pk_bf16_f32 v171, v116, v117
	v_cvt_pk_bf16_f32 v172, v106, v107
	v_cvt_pk_bf16_f32 v173, v108, v109
	s_nop 1
	v_permlane16_swap_b32 v170, v172
	v_permlane16_swap_b32 v171, v173
	s_nop 1
	global_store_dwordx4 v[184:185], v[170:173], off
	v_mul_f32_e32 v174, 0xbfb8aa3b, v102
	v_mul_f32_e32 v175, 0xbfb8aa3b, v103
	v_mul_f32_e32 v176, 0xbfb8aa3b, v104
	v_mul_f32_e32 v177, 0xbfb8aa3b, v105
	v_mul_f32_e32 v178, 0xbfb8aa3b, v94
	v_mul_f32_e32 v179, 0xbfb8aa3b, v95
	v_mul_f32_e32 v180, 0xbfb8aa3b, v96
	v_mul_f32_e32 v181, 0xbfb8aa3b, v97
	v_exp_f32_e32 v174, v174
	v_exp_f32_e32 v175, v175
	v_exp_f32_e32 v176, v176
	v_exp_f32_e32 v177, v177
	v_exp_f32_e32 v178, v178
	v_exp_f32_e32 v179, v179
	v_exp_f32_e32 v180, v180
	v_exp_f32_e32 v181, v181
	v_add_f32_e32 v174, 1.0, v174
	v_add_f32_e32 v175, 1.0, v175
	v_add_f32_e32 v176, 1.0, v176
	v_add_f32_e32 v177, 1.0, v177
	v_add_f32_e32 v178, 1.0, v178
	v_add_f32_e32 v179, 1.0, v179
	v_add_f32_e32 v180, 1.0, v180
	v_add_f32_e32 v181, 1.0, v181
	v_rcp_f32_e32 v174, v174
	v_rcp_f32_e32 v175, v175
	v_rcp_f32_e32 v176, v176
	v_rcp_f32_e32 v177, v177
	v_rcp_f32_e32 v178, v178
	v_rcp_f32_e32 v179, v179
	v_rcp_f32_e32 v180, v180
	v_rcp_f32_e32 v181, v181
	v_add_u32_e32 v8, 0x16000, v142
	v_pk_mul_f32 v[102:103], v[102:103], v[174:175]
	v_pk_mul_f32 v[104:105], v[104:105], v[176:177]
	v_pk_mul_f32 v[94:95], v[94:95], v[178:179]
	v_pk_mul_f32 v[96:97], v[96:97], v[180:181]
	v_lshl_add_u64 v[182:183], v[8:9], 1, s[52:53]
	v_pk_mul_f32 v[98:99], v[98:99], v[102:103]
	v_pk_mul_f32 v[100:101], v[100:101], v[104:105]
	v_pk_mul_f32 v[90:91], v[90:91], v[94:95]
	v_pk_mul_f32 v[92:93], v[92:93], v[96:97]
	v_cvt_pk_bf16_f32 v166, v98, v99
	v_cvt_pk_bf16_f32 v167, v100, v101
	v_cvt_pk_bf16_f32 v168, v90, v91
	v_cvt_pk_bf16_f32 v169, v92, v93
	s_nop 1
	v_permlane16_swap_b32 v166, v168
	v_permlane16_swap_b32 v167, v169
	s_nop 1
	global_store_dwordx4 v[182:183], v[166:169], off
	v_mul_f32_e32 v174, 0xbfb8aa3b, v86
	v_mul_f32_e32 v175, 0xbfb8aa3b, v87
	v_mul_f32_e32 v176, 0xbfb8aa3b, v88
	v_mul_f32_e32 v177, 0xbfb8aa3b, v89
	v_mul_f32_e32 v178, 0xbfb8aa3b, v78
	v_mul_f32_e32 v179, 0xbfb8aa3b, v79
	v_mul_f32_e32 v180, 0xbfb8aa3b, v80
	v_mul_f32_e32 v181, 0xbfb8aa3b, v81
	v_exp_f32_e32 v174, v174
	v_exp_f32_e32 v175, v175
	v_exp_f32_e32 v176, v176
	v_exp_f32_e32 v177, v177
	v_exp_f32_e32 v178, v178
	v_exp_f32_e32 v179, v179
	v_exp_f32_e32 v180, v180
	v_exp_f32_e32 v181, v181
	v_add_f32_e32 v174, 1.0, v174
	v_add_f32_e32 v175, 1.0, v175
	v_add_f32_e32 v176, 1.0, v176
	v_add_f32_e32 v177, 1.0, v177
	v_add_f32_e32 v178, 1.0, v178
	v_add_f32_e32 v179, 1.0, v179
	v_add_f32_e32 v180, 1.0, v180
	v_add_f32_e32 v181, 1.0, v181
	v_rcp_f32_e32 v174, v174
	v_rcp_f32_e32 v175, v175
	v_rcp_f32_e32 v176, v176
	v_rcp_f32_e32 v177, v177
	v_rcp_f32_e32 v178, v178
	v_rcp_f32_e32 v179, v179
	v_rcp_f32_e32 v180, v180
	v_rcp_f32_e32 v181, v181
	v_add_u32_e32 v8, 0x21000, v142
	v_pk_mul_f32 v[86:87], v[86:87], v[174:175]
	v_pk_mul_f32 v[88:89], v[88:89], v[176:177]
	v_pk_mul_f32 v[78:79], v[78:79], v[178:179]
	v_pk_mul_f32 v[80:81], v[80:81], v[180:181]
	v_lshl_add_u64 v[184:185], v[8:9], 1, s[52:53]
	v_pk_mul_f32 v[82:83], v[82:83], v[86:87]
	v_pk_mul_f32 v[84:85], v[84:85], v[88:89]
	v_pk_mul_f32 v[74:75], v[74:75], v[78:79]
	v_pk_mul_f32 v[76:77], v[76:77], v[80:81]
	v_cvt_pk_bf16_f32 v170, v82, v83
	v_cvt_pk_bf16_f32 v171, v84, v85
	v_cvt_pk_bf16_f32 v172, v74, v75
	v_cvt_pk_bf16_f32 v173, v76, v77
	s_nop 1
	v_permlane16_swap_b32 v170, v172
	v_permlane16_swap_b32 v171, v173
	s_nop 1
	global_store_dwordx4 v[184:185], v[170:173], off
	v_mul_f32_e32 v174, 0xbfb8aa3b, v70
	v_mul_f32_e32 v175, 0xbfb8aa3b, v71
	v_mul_f32_e32 v176, 0xbfb8aa3b, v72
	v_mul_f32_e32 v177, 0xbfb8aa3b, v73
	v_mul_f32_e32 v178, 0xbfb8aa3b, v62
	v_mul_f32_e32 v179, 0xbfb8aa3b, v63
	v_mul_f32_e32 v180, 0xbfb8aa3b, v64
	v_mul_f32_e32 v181, 0xbfb8aa3b, v65
	v_exp_f32_e32 v174, v174
	v_exp_f32_e32 v175, v175
	v_exp_f32_e32 v176, v176
	v_exp_f32_e32 v177, v177
	v_exp_f32_e32 v178, v178
	v_exp_f32_e32 v179, v179
	v_exp_f32_e32 v180, v180
	v_exp_f32_e32 v181, v181
	v_add_f32_e32 v174, 1.0, v174
	v_add_f32_e32 v175, 1.0, v175
	v_add_f32_e32 v176, 1.0, v176
	v_add_f32_e32 v177, 1.0, v177
	v_add_f32_e32 v178, 1.0, v178
	v_add_f32_e32 v179, 1.0, v179
	v_add_f32_e32 v180, 1.0, v180
	v_add_f32_e32 v181, 1.0, v181
	v_rcp_f32_e32 v174, v174
	v_rcp_f32_e32 v175, v175
	v_rcp_f32_e32 v176, v176
	v_rcp_f32_e32 v177, v177
	v_rcp_f32_e32 v178, v178
	v_rcp_f32_e32 v179, v179
	v_rcp_f32_e32 v180, v180
	v_rcp_f32_e32 v181, v181
	v_add_u32_e32 v8, 0x2c000, v142
	v_pk_mul_f32 v[70:71], v[70:71], v[174:175]
	v_pk_mul_f32 v[72:73], v[72:73], v[176:177]
	v_pk_mul_f32 v[62:63], v[62:63], v[178:179]
	v_pk_mul_f32 v[64:65], v[64:65], v[180:181]
	v_lshl_add_u64 v[182:183], v[8:9], 1, s[52:53]
	v_pk_mul_f32 v[66:67], v[66:67], v[70:71]
	v_pk_mul_f32 v[68:69], v[68:69], v[72:73]
	v_pk_mul_f32 v[58:59], v[58:59], v[62:63]
	v_pk_mul_f32 v[60:61], v[60:61], v[64:65]
	v_cvt_pk_bf16_f32 v166, v66, v67
	v_cvt_pk_bf16_f32 v167, v68, v69
	v_cvt_pk_bf16_f32 v168, v58, v59
	v_cvt_pk_bf16_f32 v169, v60, v61
	s_nop 1
	v_permlane16_swap_b32 v166, v168
	v_permlane16_swap_b32 v167, v169
; __device__ __forceinline__ float siluf_(float x) { return x * __builtin_amdgcn_rcpf(1.f + __expf(-x)); }
;     ...
;         } else if constexpr (EPI == EPI_SWIGLU) {
; #pragma unroll
;           for (int np = 0; np < 2; np++) {
;             const unsigned hc = ((unsigned)(n0 + wn * 64) >> 1) + np * 16 + fq * 4;
;             const f32x4 g = acc[mi][2 * np], u = acc[mi][2 * np + 1];
;             uint2 o;
;             o.x = pack2(siluf_(g[0]) * u[0], siluf_(g[1]) * u[1]);
;             o.y = pack2(siluf_(g[2]) * u[2], siluf_(g[3]) * u[3]);
;             *(uint2*)(e.b0 + (row * (unsigned)DFF + hc)) = o;
;           }
	s_nop 1
	global_store_dwordx4 v[182:183], v[166:169], off
	v_mul_f32_e32 v174, 0xbfb8aa3b, v54
	v_mul_f32_e32 v175, 0xbfb8aa3b, v55
	v_mul_f32_e32 v176, 0xbfb8aa3b, v56
	v_mul_f32_e32 v177, 0xbfb8aa3b, v57
	v_mul_f32_e32 v178, 0xbfb8aa3b, v46
	v_mul_f32_e32 v179, 0xbfb8aa3b, v47
	v_mul_f32_e32 v180, 0xbfb8aa3b, v48
	v_mul_f32_e32 v181, 0xbfb8aa3b, v49
	v_exp_f32_e32 v174, v174
	v_exp_f32_e32 v175, v175
	v_exp_f32_e32 v176, v176
	v_exp_f32_e32 v177, v177
	v_exp_f32_e32 v178, v178
	v_exp_f32_e32 v179, v179
	v_exp_f32_e32 v180, v180
	v_exp_f32_e32 v181, v181
	v_add_f32_e32 v174, 1.0, v174
	v_add_f32_e32 v175, 1.0, v175
	v_add_f32_e32 v176, 1.0, v176
	v_add_f32_e32 v177, 1.0, v177
	v_add_f32_e32 v178, 1.0, v178
	v_add_f32_e32 v179, 1.0, v179
	v_add_f32_e32 v180, 1.0, v180
	v_add_f32_e32 v181, 1.0, v181
	v_rcp_f32_e32 v174, v174
	v_rcp_f32_e32 v175, v175
	v_rcp_f32_e32 v176, v176
	v_rcp_f32_e32 v177, v177
	v_rcp_f32_e32 v178, v178
	v_rcp_f32_e32 v179, v179
	v_rcp_f32_e32 v180, v180
	v_rcp_f32_e32 v181, v181
	v_add_u32_e32 v8, 0x37000, v142
	v_pk_mul_f32 v[54:55], v[54:55], v[174:175]
	v_pk_mul_f32 v[56:57], v[56:57], v[176:177]
	v_pk_mul_f32 v[46:47], v[46:47], v[178:179]
	v_pk_mul_f32 v[48:49], v[48:49], v[180:181]
	v_lshl_add_u64 v[184:185], v[8:9], 1, s[52:53]
	v_pk_mul_f32 v[50:51], v[50:51], v[54:55]
	v_pk_mul_f32 v[52:53], v[52:53], v[56:57]
	v_pk_mul_f32 v[42:43], v[42:43], v[46:47]
	v_pk_mul_f32 v[44:45], v[44:45], v[48:49]
	v_cvt_pk_bf16_f32 v170, v50, v51
	v_cvt_pk_bf16_f32 v171, v52, v53
	v_cvt_pk_bf16_f32 v172, v42, v43
	v_cvt_pk_bf16_f32 v173, v44, v45
	s_nop 1
	v_permlane16_swap_b32 v170, v172
	v_permlane16_swap_b32 v171, v173
	s_nop 1
	global_store_dwordx4 v[184:185], v[170:173], off
	v_mul_f32_e32 v174, 0xbfb8aa3b, v38
	v_mul_f32_e32 v175, 0xbfb8aa3b, v39
	v_mul_f32_e32 v176, 0xbfb8aa3b, v40
	v_mul_f32_e32 v177, 0xbfb8aa3b, v41
	v_mul_f32_e32 v178, 0xbfb8aa3b, v30
	v_mul_f32_e32 v179, 0xbfb8aa3b, v31
	v_mul_f32_e32 v180, 0xbfb8aa3b, v32
	v_mul_f32_e32 v181, 0xbfb8aa3b, v33
	v_exp_f32_e32 v174, v174
	v_exp_f32_e32 v175, v175
	v_exp_f32_e32 v176, v176
	v_exp_f32_e32 v177, v177
	v_exp_f32_e32 v178, v178
	v_exp_f32_e32 v179, v179
	v_exp_f32_e32 v180, v180
	v_exp_f32_e32 v181, v181
	v_add_f32_e32 v174, 1.0, v174
	v_add_f32_e32 v175, 1.0, v175
	v_add_f32_e32 v176, 1.0, v176
	v_add_f32_e32 v177, 1.0, v177
	v_add_f32_e32 v178, 1.0, v178
	v_add_f32_e32 v179, 1.0, v179
	v_add_f32_e32 v180, 1.0, v180
	v_add_f32_e32 v181, 1.0, v181
	v_rcp_f32_e32 v174, v174
	v_rcp_f32_e32 v175, v175
	v_rcp_f32_e32 v176, v176
	v_rcp_f32_e32 v177, v177
	v_rcp_f32_e32 v178, v178
	v_rcp_f32_e32 v179, v179
	v_rcp_f32_e32 v180, v180
	v_rcp_f32_e32 v181, v181
	v_add_u32_e32 v8, 0x42000, v142
	v_pk_mul_f32 v[38:39], v[38:39], v[174:175]
	v_pk_mul_f32 v[40:41], v[40:41], v[176:177]
	v_pk_mul_f32 v[30:31], v[30:31], v[178:179]
	v_pk_mul_f32 v[32:33], v[32:33], v[180:181]
	v_lshl_add_u64 v[182:183], v[8:9], 1, s[52:53]
	v_pk_mul_f32 v[34:35], v[34:35], v[38:39]
	v_pk_mul_f32 v[36:37], v[36:37], v[40:41]
	v_pk_mul_f32 v[26:27], v[26:27], v[30:31]
	v_pk_mul_f32 v[28:29], v[28:29], v[32:33]
	v_cvt_pk_bf16_f32 v166, v34, v35
	v_cvt_pk_bf16_f32 v167, v36, v37
	v_cvt_pk_bf16_f32 v168, v26, v27
	v_cvt_pk_bf16_f32 v169, v28, v29
	s_nop 1
	v_permlane16_swap_b32 v166, v168
	v_permlane16_swap_b32 v167, v169
	s_nop 1
	global_store_dwordx4 v[182:183], v[166:169], off
	v_mul_f32_e32 v174, 0xbfb8aa3b, v22
	v_mul_f32_e32 v175, 0xbfb8aa3b, v23
	v_mul_f32_e32 v176, 0xbfb8aa3b, v24
	v_mul_f32_e32 v177, 0xbfb8aa3b, v25
	v_mul_f32_e32 v178, 0xbfb8aa3b, v14
	v_mul_f32_e32 v179, 0xbfb8aa3b, v15
	v_mul_f32_e32 v180, 0xbfb8aa3b, v16
	v_mul_f32_e32 v181, 0xbfb8aa3b, v17
	v_exp_f32_e32 v174, v174
	v_exp_f32_e32 v175, v175
	v_exp_f32_e32 v176, v176
	v_exp_f32_e32 v177, v177
	v_exp_f32_e32 v178, v178
	v_exp_f32_e32 v179, v179
	v_exp_f32_e32 v180, v180
	v_exp_f32_e32 v181, v181
	v_add_f32_e32 v174, 1.0, v174
	v_add_f32_e32 v175, 1.0, v175
	v_add_f32_e32 v176, 1.0, v176
	v_add_f32_e32 v177, 1.0, v177
	v_add_f32_e32 v178, 1.0, v178
	v_add_f32_e32 v179, 1.0, v179
	v_add_f32_e32 v180, 1.0, v180
	v_add_f32_e32 v181, 1.0, v181
	v_rcp_f32_e32 v174, v174
	v_rcp_f32_e32 v175, v175
	v_rcp_f32_e32 v176, v176
	v_rcp_f32_e32 v177, v177
	v_rcp_f32_e32 v178, v178
	v_rcp_f32_e32 v179, v179
	v_rcp_f32_e32 v180, v180
	v_rcp_f32_e32 v181, v181
	v_add_u32_e32 v8, 0x4d000, v142
	v_pk_mul_f32 v[22:23], v[22:23], v[174:175]
	v_pk_mul_f32 v[24:25], v[24:25], v[176:177]
	v_pk_mul_f32 v[14:15], v[14:15], v[178:179]
	v_pk_mul_f32 v[16:17], v[16:17], v[180:181]
	v_lshl_add_u64 v[184:185], v[8:9], 1, s[52:53]
	v_pk_mul_f32 v[18:19], v[18:19], v[22:23]
	v_pk_mul_f32 v[20:21], v[20:21], v[24:25]
	v_pk_mul_f32 v[10:11], v[10:11], v[14:15]
	v_pk_mul_f32 v[12:13], v[12:13], v[16:17]
	v_cvt_pk_bf16_f32 v170, v18, v19
	v_cvt_pk_bf16_f32 v171, v20, v21
	v_cvt_pk_bf16_f32 v172, v10, v11
	v_cvt_pk_bf16_f32 v173, v12, v13
	s_nop 1
	v_permlane16_swap_b32 v170, v172
	v_permlane16_swap_b32 v171, v173
	s_nop 1
	global_store_dwordx4 v[184:185], v[170:173], off
	s_setprio 0
	v_readlane_b32 vcc_lo, v244, 27
	s_nop 0
	s_bitcmp1_b32 vcc_lo, 8
	s_cbranch_scc0 .Lsw_prio_old
	s_setprio 1
.Lsw_prio_old:
	s_add_i32 s6, s6, 1
	s_mov_b64 s[4:5], 0
	s_branch .LBB0_2615
